# batched the serialized gate loads in the mixer-A unit prologue
# baseline (speedup 1.0000x reference)
; __device__ __forceinline__ float bf2f(unsigned short v) { return __uint_as_float(((unsigned)v) << 16); }
; __device__ __forceinline__ unsigned src_off(int w, int lane, int ldB) { const int R = 8 * w + (lane >> 3), cch = (lane & 7) ^ swz(R); return (unsigned)(R * ldB + cch * 16); }
; __device__ __forceinline__ void unitA(unsigned char* lds, PG8_LAS unsigned char* lds3, const Args& a, int b, int g, int T) {
;     ...
;     int tq[2]; bf16x8 q[2][2];
;     f32x4* stash = (f32x4*)(lds + OFF_STASH);
; #pragma unroll
;     for (int cg_ = 0; cg_ < 2; ++cg_) {
;         tq[cg_] = t0 + 8 * w + 4 * cg_ + (c >> 2);
;         const bf16_t* rowp = a.PQ + (size_t)(b * SEQ + tq[cg_]) * PQ_LD;
; #pragma unroll
;         for (int dc = 0; dc < 2; ++dc) q[cg_][dc] = *(const bf16x8*)(rowp + H * 64 + 32 * dc + 8 * fq);
;     }
; #pragma unroll
;     for (int cg_ = 0; cg_ < 2; ++cg_)
; #pragma unroll
;         for (int dc = 0; dc < 2; ++dc) asm volatile("" : "+v"(q[cg_][dc]));
;     float gatev[3][2];
; #pragma unroll
;     for (int cg_ = 0; cg_ < 2; ++cg_)
; #pragma unroll
;         for (int br = 0; br < 3; ++br) { gatev[br][cg_] = bf2f(a.PQ[(size_t)(b * SEQ + tq[cg_]) * PQ_LD + 1280 + br * 8 + H]); asm volatile("" : "+v"(gatev[br][cg_])); }
;     ...
;     const float farb = btab[128 * 16 + H];
;     const unsigned soff = src_off(w, lane, 128);
;     __syncthreads();
.LBB0_2228:
	v_mov_b32_e32 v133, v198
	s_lshl_b32 s1, s36, 2
	v_ashrrev_i32_e32 v141, 6, v133
	v_and_b32_e32 v134, 3, v133
	v_lshlrev_b32_e32 v132, 3, v141
	v_and_or_b32 v19, s1, 4, v134
	v_add_u32_e32 v0, s28, v132
	v_bfe_u32 v135, v133, 2, 2
	s_lshl_b32 s1, s36, 12
	v_or_b32_e32 v4, v0, v135
	s_and_b32 s1, s1, 0x7fffe000
	v_lshlrev_b32_e32 v0, 7, v19
	v_lshl_add_u64 v[2:3], s[70:71], 0, v[0:1]
	v_and_b32_e32 v0, 48, v133
	v_add_u32_e32 v152, s1, v4
	v_lshl_add_u64 v[2:3], v[2:3], 0, v[0:1]
	v_add_u32_e32 v150, 4, v152
	v_mad_i64_i32 v[6:7], s[8:9], v152, s60, v[2:3]
	v_mad_i64_i32 v[14:15], s[8:9], v150, s60, v[2:3]
	global_load_dwordx4 v[2:5], v[6:7], off
	s_nop 0
	global_load_dwordx4 v[6:9], v[6:7], off offset:64
	s_nop 0
	global_load_dwordx4 v[10:13], v[14:15], off
	s_nop 0
	global_load_dwordx4 v[14:17], v[14:15], off offset:64
	v_mov_b64_e32 v[20:21], s[70:71]
	v_lshlrev_b32_e32 v0, 1, v19
	v_mad_i64_i32 v[22:23], s[8:9], v152, s60, v[20:21]
	v_lshl_add_u64 v[22:23], v[22:23], 0, v[0:1]
	v_mad_i64_i32 v[20:21], s[8:9], v150, s60, v[20:21]
	v_lshl_add_u64 v[20:21], v[20:21], 0, v[0:1]
	v_lshl_add_u32 v177, v19, 2, s61
	s_movk_i32 s1, 0x2040
	v_readfirstlane_b32 s4, v141
	v_cmp_gt_i32_e32 vcc, s1, v133
	global_load_ushort v144, v[22:23], off offset:2560
	global_load_ushort v139, v[22:23], off offset:2576
	global_load_ushort v174, v[22:23], off offset:2592
	global_load_ushort v143, v[20:21], off offset:2560
	global_load_ushort v138, v[20:21], off offset:2576
	global_load_ushort v173, v[20:21], off offset:2592
	s_waitcnt vmcnt(0)
	v_lshlrev_b32_e32 v144, 16, v144
	v_lshlrev_b32_e32 v139, 16, v139
	v_lshlrev_b32_e32 v174, 16, v174
	v_lshlrev_b32_e32 v143, 16, v143
	v_lshlrev_b32_e32 v138, 16, v138
	v_lshlrev_b32_e32 v173, 16, v173
	ds_read_b32 v18, v177 offset:8192
	s_waitcnt lgkmcnt(0)
	s_barrier
	s_and_saveexec_b64 s[8:9], vcc
	s_cbranch_execz .LBB0_2231
	v_add_u32_e32 v0, 0xfffffe00, v133
	v_lshl_add_u32 v20, v133, 2, s65
	s_mov_b64 s[10:11], 0
